# att25 = att14 + in-proj GEMM unit order with WGM=4 instead of 8 (4 m-tiles x 8 n-tiles per XCD round): L2 locality experiment
# speedup vs baseline: 1.0043x; 1.0033x over previous
.LBB0_208:
	s_add_u32 s28, s22, 0x3000000
	s_addc_u32 s29, s23, 0
	v_mov_b32_e32 v10, v244
	s_cmpk_gt_i32 s16, 0xdff
	v_readfirstlane_b32 s3, v10
	s_cbranch_scc1 .LBB0_224
	v_lshlrev_b32_e32 v0, 4, v10
	v_add_u32_e32 v1, 0x2000, v0
	v_ashrrev_i32_e32 v2, 31, v1
	v_lshrrev_b32_e32 v2, 22, v2
	v_add_u32_e32 v2, v1, v2
	v_ashrrev_i32_e32 v8, 10, v2
	v_mul_i32_i24_e32 v2, 0x400, v8
	v_sub_u32_e32 v1, v1, v2
	v_lshrrev_b32_e32 v2, 4, v1
	v_bitop3_b32 v1, v2, v1, 32 bitop3:0x6c
	v_ashrrev_i32_e32 v2, 31, v1
	v_lshrrev_b32_e32 v2, 26, v2
	v_add_u32_e32 v2, v1, v2
	v_lshlrev_b32_e32 v3, 3, v8
	v_ashrrev_i32_e32 v9, 6, v2
	v_and_b32_e32 v3, -16, v3
	v_add_u32_e32 v3, v9, v3
	v_and_b32_e32 v4, 3, v9
	s_mov_b32 s0, 0x1fffe0
	v_lshrrev_b32_e32 v5, 2, v3
	v_lshlrev_b32_e32 v6, 1, v3
	v_and_b32_e32 v2, 0xc0, v2
	v_and_or_b32 v4, v3, s0, v4
	v_and_b32_e32 v5, 4, v5
	v_and_b32_e32 v6, 24, v6
	v_sub_u32_e32 v1, v1, v2
	v_mov_b32_e32 v2, 1
	v_or3_b32 v4, v4, v5, v6
	v_lshlrev_b32_e32 v5, 5, v8
	v_ashrrev_i16_sdwa v1, v2, sext(v1) dst_sel:DWORD dst_unused:UNUSED_PAD src0_sel:DWORD src1_sel:BYTE_0
	v_and_b32_e32 v5, 32, v5
	v_bfe_i32 v11, v1, 0, 16
	v_add_lshl_u32 v1, v5, v11, 1
	v_lshl_add_u32 v128, v4, 11, v1
	v_lshl_add_u32 v130, v3, 11, v1
	v_bfe_i32 v1, v10, 27, 1
	v_lshrrev_b32_e32 v1, 22, v1
	v_add_u32_e32 v1, v0, v1
	v_and_b32_e32 v1, 0xfffffc00, v1
	v_sub_u32_e32 v0, v0, v1
	v_lshrrev_b32_e32 v1, 4, v0
	v_ashrrev_i32_e32 v3, 31, v10
	v_bitop3_b32 v0, v1, v0, 32 bitop3:0x6c
	v_lshrrev_b32_e32 v3, 26, v3
	v_ashrrev_i32_e32 v1, 31, v0
	v_add_u32_e32 v3, v10, v3
	v_lshrrev_b32_e32 v1, 26, v1
	v_ashrrev_i32_e32 v13, 6, v3
	v_add_u32_e32 v1, v0, v1
	v_lshlrev_b32_e32 v3, 3, v13
	v_ashrrev_i32_e32 v12, 6, v1
	v_and_b32_e32 v3, -16, v3
	v_add_u32_e32 v3, v12, v3
	v_and_b32_e32 v4, 3, v12
	s_ashr_i32 s18, s16, 31
	v_and_or_b32 v4, v3, s0, v4
	s_lshr_b32 s0, s18, 29
	s_add_i32 s0, s16, s0
	s_ashr_i32 s10, s3, 6
	s_ashr_i32 s1, s0, 3
	s_and_b32 s0, s0, -8
	s_ashr_i32 s12, s3, 8
	s_lshl_b32 s17, s10, 10
	s_sub_i32 s0, s16, s0
	s_cmp_lt_i32 s0, 0
	s_movk_i32 s19, 0x1c1
	s_cselect_b32 s2, s19, 0x1c0
	s_mul_i32 s0, s0, s2
	s_add_i32 s0, s0, s1
	s_mul_hi_i32 s1, s0, 0x92492493
	s_add_i32 s1, s1, s0
	s_lshr_b32 s2, s1, 31
	s_ashr_i32 s1, s1, 6
	s_add_i32 s1, s1, s2
	s_lshl_b32 s8, s1, 2
	s_mulk_i32 s1, 0x70
	s_sub_i32 s0, s0, s1
	s_sext_i32_i16 s1, s0
	s_bfe_u32 s1, s1, 0x2001e
	s_add_i32 s1, s0, s1
	s_sext_i32_i16 s2, s1
	s_and_b32 s1, s1, 0xfffc
	s_sub_i32 s0, s0, s1
	s_sext_i32_i16 s0, s0
	v_lshrrev_b32_e32 v5, 2, v3
	v_lshlrev_b32_e32 v6, 1, v3
	v_and_b32_e32 v1, 0xc0, v1
	s_lshr_b32 s2, s2, 2
	s_add_i32 s42, s8, s0
	v_and_b32_e32 v5, 4, v5
	v_and_b32_e32 v6, 24, v6
	v_sub_u32_e32 v0, v0, v1
	s_ashr_i32 s43, s42, 31
	s_bfe_i64 s[8:9], s[2:3], 0x100000
	v_or3_b32 v4, v4, v5, v6
	v_lshlrev_b32_e32 v5, 5, v13
	v_ashrrev_i16_sdwa v0, v2, sext(v0) dst_sel:DWORD dst_unused:UNUSED_PAD src0_sel:DWORD src1_sel:BYTE_0
	s_lshl_b64 s[0:1], s[42:43], 19
	s_lshl_b64 s[8:9], s[8:9], 19
	v_and_b32_e32 v5, 32, v5
	v_bfe_i32 v14, v0, 0, 16
	s_add_u32 s54, s6, s8
	v_add_lshl_u32 v0, v5, v14, 1
	s_addc_u32 s55, s7, s9
	s_add_i32 s26, s17, 0
	v_lshl_add_u32 v132, v4, 11, v0
	s_add_i32 m0, s26, 0x10000
	v_lshl_add_u32 v134, v3, 11, v0
	global_load_lds_dwordx4 v132, s[54:55]
	s_add_i32 m0, s26, 0x12000
	s_add_u32 s8, s54, 0x40000
	global_load_lds_dwordx4 v128, s[54:55]
	s_addc_u32 s9, s55, 0
	s_add_i32 m0, s26, 0x14000
	v_mov_b32_e32 v133, 0
	global_load_lds_dwordx4 v132, s[8:9]
	s_add_i32 m0, s26, 0x16000
	s_add_u32 s0, s20, s0
	s_addc_u32 s1, s21, s1
	s_add_i32 s27, s26, 0x2000
	global_load_lds_dwordx4 v128, s[8:9]
	s_mov_b32 m0, s26
	s_add_u32 s8, s0, 0x40000
	global_load_lds_dwordx4 v134, s[0:1]
	s_mov_b32 m0, s27
	s_addc_u32 s9, s1, 0
	s_add_i32 s33, s26, 0x4000
	global_load_lds_dwordx4 v130, s[0:1]
	s_mov_b32 m0, s33
	s_add_i32 s34, s26, 0x6000
	global_load_lds_dwordx4 v134, s[8:9]
	s_mov_b32 m0, s34
	v_mov_b32_e32 v129, v133
	global_load_lds_dwordx4 v130, s[8:9]
	v_mov_b32_e32 v135, v133
	v_mov_b32_e32 v131, v133
	s_cmp_eq_u32 s12, 1
	s_mov_b32 s35, 0
	v_lshl_add_u64 v[6:7], s[54:55], 0, v[132:133]
	v_lshl_add_u64 v[2:3], s[54:55], 0, v[128:129]
	v_lshl_add_u64 v[0:1], s[0:1], 0, v[134:135]
	s_cselect_b64 s[8:9], -1, 0
	s_cmp_lg_u32 s12, 1
	v_lshl_add_u64 v[4:5], s[0:1], 0, v[130:131]
	s_cbranch_scc1 .LBB0_211
	s_barrier

.LBB0_214:
	s_add_i32 s35, s35, 1
	s_mul_i32 s2, s35, s45
	s_mul_hi_u32 s3, s35, s46
	s_add_i32 s3, s3, s2
	s_mul_i32 s2, s35, s46
	s_add_u32 s24, s2, s16
	s_addc_u32 s25, s3, s18
	v_cmp_gt_i64_e32 vcc, s[24:25], v[142:143]
	v_cmp_lt_i64_e64 s[2:3], s[24:25], v[140:141]
	s_cbranch_vccnz .LBB0_216
	s_ashr_i32 s14, s24, 31
	s_lshr_b32 s14, s14, 29
	s_add_i32 s14, s24, s14
	s_ashr_i32 s15, s14, 3
	s_and_b32 s14, s14, -8
	s_sub_i32 s14, s24, s14
	s_cmp_lt_i32 s14, 0
	s_cselect_b32 s24, s19, 0x1c0
	s_mul_i32 s14, s14, s24
	s_add_i32 s14, s14, s15
	s_mul_hi_i32 s15, s14, 0x92492493
	s_add_i32 s15, s15, s14
	s_lshr_b32 s24, s15, 31
	s_ashr_i32 s15, s15, 6
	s_add_i32 s15, s15, s24
	s_lshl_b32 s24, s15, 2
	s_sub_i32 s25, 0x80, s24
	s_min_i32 s25, s25, 4
	s_abs_i32 s30, s25
	v_cvt_f32_u32_e32 v0, s30
	s_sub_i32 s36, 0, s30
	s_mulk_i32 s15, 0x70
	s_sub_i32 s15, s14, s15
	v_rcp_iflag_f32_e32 v0, v0
	s_abs_i32 s14, s15
	s_xor_b32 s31, s15, s25
	s_ashr_i32 s31, s31, 31
	v_mul_f32_e32 v0, 0x4f7ffffe, v0
	v_cvt_u32_f32_e32 v0, v0
	s_nop 0
	v_readfirstlane_b32 s37, v0
	s_mul_i32 s36, s36, s37
	s_mul_hi_u32 s36, s37, s36
	s_add_i32 s37, s37, s36
	s_mul_hi_u32 s36, s14, s37
	s_mul_i32 s37, s36, s30
	s_sub_i32 s14, s14, s37
	s_add_i32 s38, s36, 1
	s_sub_i32 s37, s14, s30
	s_cmp_ge_u32 s14, s30
	s_cselect_b32 s36, s38, s36
	s_cselect_b32 s14, s37, s14
	s_add_i32 s37, s36, 1
	s_cmp_ge_u32 s14, s30
	s_cselect_b32 s14, s37, s36
	s_xor_b32 s14, s14, s31
	s_sub_i32 s14, s14, s31
	s_mul_i32 s25, s14, s25
	s_sub_i32 s15, s15, s25
	s_add_i32 s30, s24, s15
